# forget-sample units: wave 0 new-keys tile issues its cs load together with the K/V loads instead of after waiting for them
# baseline (speedup 1.0000x reference)
.LBB0_513:
	s_andn2_b64 vcc, exec, s[8:9]
	s_cbranch_vccnz .LBB0_531
	s_ashr_i32 s7, s6, 31
	s_lshl_b64 s[8:9], s[6:7], 10
	v_readlane_b32 s10, v253, 8
	v_readlane_b32 s11, v253, 9
	s_add_u32 s8, s10, s8
	s_addc_u32 s9, s11, s9
	s_add_u32 s8, s8, s2
	s_addc_u32 s9, s9, 0
	v_mov_b32_e32 v213, v4
	v_lshl_add_u64 v[2:3], s[8:9], 0, v[212:213]
	v_mov_b32_e32 v221, v4
	v_lshl_add_u64 v[2:3], v[2:3], 0, v[220:221]
	s_waitcnt vmcnt(0)
	v_mov_b32_e32 v6, 0
	v_mov_b32_e32 v10, 0
	v_mov_b32_e32 v11, 0
	v_mov_b32_e32 v12, 0
	v_mov_b32_e32 v13, 0
	v_lshlrev_b32_e32 v102, 2, v198
	v_mov_b32_e32 v103, v4
	v_lshl_add_u64 v[102:103], s[0:1], 0, v[102:103]
	v_add_co_u32_e32 v102, vcc, 0x2000, v102
	s_nop 1
	v_addc_co_u32_e32 v103, vcc, 0, v103, vcc
	s_mov_b64 s[98:99], exec
	s_and_b64 exec, exec, s[28:29]
	global_load_dword v104, v[102:103], off
	s_mov_b64 exec, s[98:99]
	s_and_saveexec_b64 s[8:9], s[28:29]
	s_cbranch_execz .LBB0_516
	global_load_dwordx4 v[10:13], v[2:3], off

.LBB0_526:
	s_or_b64 exec, exec, s[8:9]
	s_waitcnt vmcnt(1)
	ds_write_b128 v3, v[66:69] offset:32
	s_waitcnt vmcnt(0)
	ds_write_b128 v3, v[70:73] offset:48
	s_and_saveexec_b64 s[6:7], s[28:29]
	s_cbranch_execz .LBB0_528
	v_mov_b32_e32 v2, v104

	.amdhsa_kernel _Z8mega_fwd4Args
		.amdhsa_group_segment_fixed_size 0
		.amdhsa_private_segment_fixed_size 0
		.amdhsa_kernarg_size 512
		.amdhsa_user_sgpr_count 2
		.amdhsa_user_sgpr_dispatch_ptr 0
		.amdhsa_user_sgpr_queue_ptr 0
		.amdhsa_user_sgpr_kernarg_segment_ptr 1
		.amdhsa_user_sgpr_dispatch_id 0
		.amdhsa_user_sgpr_kernarg_preload_length 0
		.amdhsa_user_sgpr_kernarg_preload_offset 0
		.amdhsa_user_sgpr_private_segment_size 0
		.amdhsa_uses_dynamic_stack 0
		.amdhsa_enable_private_segment 0
		.amdhsa_system_sgpr_workgroup_id_x 1
		.amdhsa_system_sgpr_workgroup_id_y 0
		.amdhsa_system_sgpr_workgroup_id_z 0
		.amdhsa_system_sgpr_workgroup_info 0
		.amdhsa_system_vgpr_workitem_id 2
		.amdhsa_next_free_vgpr 256
		.amdhsa_next_free_sgpr 102
		.amdhsa_accum_offset 256
		.amdhsa_reserve_vcc 1
		.amdhsa_float_round_mode_32 0
		.amdhsa_float_round_mode_16_64 0
		.amdhsa_float_denorm_mode_32 3
		.amdhsa_float_denorm_mode_16_64 3
		.amdhsa_dx10_clamp 1
		.amdhsa_ieee_mode 1
		.amdhsa_fp16_overflow 0
		.amdhsa_tg_split 0
		.amdhsa_exception_fp_ieee_invalid_op 0
		.amdhsa_exception_fp_denorm_src 0
		.amdhsa_exception_fp_ieee_div_zero 0
		.amdhsa_exception_fp_ieee_overflow 0
		.amdhsa_exception_fp_ieee_underflow 0
		.amdhsa_exception_fp_ieee_inexact 0
		.amdhsa_exception_int_div_zero 0
	.end_amdhsa_kernel

amdhsa.kernels:
  - .agpr_count:     0
    .args:
      - .offset:         0
        .size:           256
        .value_kind:     by_value
      - .offset:         256
        .size:           4
        .value_kind:     hidden_block_count_x
      - .offset:         260
        .size:           4
        .value_kind:     hidden_block_count_y
      - .offset:         264
        .size:           4
        .value_kind:     hidden_block_count_z
      - .offset:         268
        .size:           2
        .value_kind:     hidden_group_size_x
      - .offset:         270
        .size:           2
        .value_kind:     hidden_group_size_y
      - .offset:         272
        .size:           2
        .value_kind:     hidden_group_size_z
      - .offset:         274
        .size:           2
        .value_kind:     hidden_remainder_x
      - .offset:         276
        .size:           2
        .value_kind:     hidden_remainder_y
      - .offset:         278
        .size:           2
        .value_kind:     hidden_remainder_z
      - .offset:         296
        .size:           8
        .value_kind:     hidden_global_offset_x
      - .offset:         304
        .size:           8
        .value_kind:     hidden_global_offset_y
      - .offset:         312
        .size:           8
        .value_kind:     hidden_global_offset_z
      - .offset:         320
        .size:           2
        .value_kind:     hidden_grid_dims
      - .offset:         344
        .size:           8
        .value_kind:     hidden_multigrid_sync_arg
      - .offset:         376
        .size:           4
        .value_kind:     hidden_dynamic_lds_size
    .group_segment_fixed_size: 0
    .kernarg_segment_align: 8
    .kernarg_segment_size: 512
    .language:       OpenCL C
    .language_version:
      - 2
      - 0
    .max_flat_workgroup_size: 512
    .name:           _Z8mega_fwd4Args
    .private_segment_fixed_size: 0
    .sgpr_count:     108
    .sgpr_spill_count: 209
    .symbol:         _Z8mega_fwd4Args.kd
    .uniform_work_group_size: 1
    .uses_dynamic_stack: false
    .vgpr_count:     256
    .vgpr_spill_count: 0
    .wavefront_size: 64
